# K-loop bodies 64-byte aligned so their placement no longer depends on code elsewhere
# speedup vs baseline: 1.0036x; 1.0018x over previous
.LBB0_248:
	s_mul_hi_i32 s0, s30, 0x38e38e39
	s_lshr_b32 s1, s0, 31
	s_ashr_i32 s31, s0, 4
	s_add_i32 s31, s31, s1
	v_readfirstlane_b32 s5, v128
	s_mul_i32 s0, s31, 0x48
	s_lshr_b32 s16, s5, 1
	s_sub_i32 s4, s30, s0
	s_and_b32 s16, s16, 0x1ffff80
	s_lshl_b32 s0, s4, 19
	v_or_b32_e32 v8, s16, v189
	s_and_b32 s16, s5, 0xc0
	s_lshl_b32 s5, s5, 4
	v_add_u32_e32 v0, s0, v134
	v_lshlrev_b32_e32 v153, 7, v8
	v_or_b32_e32 v8, s16, v189
	s_and_b32 s5, s5, 0x7ffffc00
	v_add_u32_e32 v1, s0, v138
	v_lshl_or_b32 v155, v8, 7, v139
	v_and_b32_e32 v8, 0xfffff870, v0
	s_mov_b32 m0, s5
	v_add_u32_e32 v2, s0, v140
	global_load_lds_dwordx4 v8, s[86:87]
	v_and_b32_e32 v1, 0xfffff870, v1
	s_add_i32 m0, s5, 0x2000
	s_lshl_b32 s1, s31, 19
	v_add_u32_e32 v3, s0, v142
	global_load_lds_dwordx4 v1, s[86:87]
	v_and_b32_e32 v1, 0xfffff870, v2
	s_add_i32 m0, s5, 0x4000
	v_add_u32_e32 v4, s1, v144
	s_add_i32 s16, s5, 0x8000
	global_load_lds_dwordx4 v1, s[86:87]
	v_and_b32_e32 v1, 0xfffff870, v3
	s_add_i32 m0, s5, 0x6000
	v_add_u32_e32 v5, s1, v146
	global_load_lds_dwordx4 v1, s[86:87]
	v_and_b32_e32 v1, 0xfffff870, v4
	s_mov_b32 m0, s16
	v_add_u32_e32 v6, s1, v148
	global_load_lds_dwordx4 v1, s[86:87]
	v_and_b32_e32 v1, 0xfffff870, v5
	s_add_i32 m0, s5, 0xa000
	v_add_u32_e32 v7, s1, v150
	global_load_lds_dwordx4 v1, s[86:87]
	v_and_b32_e32 v1, 0xfffff870, v6
	s_add_i32 m0, s5, 0xc000
	v_and_b32_e32 v136, -16, v0
	global_load_lds_dwordx4 v1, s[86:87]
	v_and_b32_e32 v1, 0xfffff870, v7
	s_add_i32 m0, s5, 0xe000
	v_add_u32_e32 v0, s0, v152
	global_load_lds_dwordx4 v1, s[86:87]
	v_lshl_add_u64 v[162:163], s[14:15], 0, v[136:137]
	v_and_b32_e32 v136, -16, v0
	v_add_u32_e32 v0, s0, v154
	v_lshl_add_u64 v[164:165], s[14:15], 0, v[136:137]
	v_and_b32_e32 v136, -16, v0
	v_add_u32_e32 v0, s0, v156
	v_lshl_add_u64 v[166:167], s[14:15], 0, v[136:137]
	v_and_b32_e32 v136, -16, v0
	v_lshl_add_u64 v[168:169], s[14:15], 0, v[136:137]
	v_and_b32_e32 v136, -16, v4
	v_add_u32_e32 v0, s1, v158
	v_lshl_add_u64 v[170:171], s[14:15], 0, v[136:137]
	v_and_b32_e32 v136, -16, v0
	s_waitcnt vmcnt(0)
	v_lshl_add_u64 v[172:173], s[14:15], 0, v[136:137]
	v_and_b32_e32 v136, -16, v6
	v_add_u32_e32 v0, s1, v160
	v_lshl_add_u64 v[174:175], s[14:15], 0, v[136:137]
	v_and_b32_e32 v136, -16, v0
	v_lshl_add_u64 v[176:177], s[14:15], 0, v[136:137]
	s_mov_b64 s[0:1], 0
	s_mov_b32 s16, s91
	v_mov_b32_e32 v56, v137
	v_mov_b32_e32 v57, v137
	v_mov_b32_e32 v58, v137
	v_mov_b32_e32 v59, v137
	v_mov_b32_e32 v0, v137
	v_mov_b32_e32 v1, v137
	v_mov_b32_e32 v2, v137
	v_mov_b32_e32 v3, v137
	v_mov_b32_e32 v64, v137
	v_mov_b32_e32 v65, v137
	v_mov_b32_e32 v66, v137
	v_mov_b32_e32 v67, v137
	v_mov_b32_e32 v68, v137
	v_mov_b32_e32 v69, v137
	v_mov_b32_e32 v70, v137
	v_mov_b32_e32 v71, v137
	v_mov_b32_e32 v4, v137
	v_mov_b32_e32 v5, v137
	v_mov_b32_e32 v6, v137
	v_mov_b32_e32 v7, v137
	v_mov_b32_e32 v8, v137
	v_mov_b32_e32 v9, v137
	v_mov_b32_e32 v10, v137
	v_mov_b32_e32 v11, v137
	v_mov_b32_e32 v72, v137
	v_mov_b32_e32 v73, v137
	v_mov_b32_e32 v74, v137
	v_mov_b32_e32 v75, v137
	v_mov_b32_e32 v76, v137
	v_mov_b32_e32 v77, v137
	v_mov_b32_e32 v78, v137
	v_mov_b32_e32 v79, v137
	v_mov_b32_e32 v12, v137
	v_mov_b32_e32 v13, v137
	v_mov_b32_e32 v14, v137
	v_mov_b32_e32 v15, v137
	v_mov_b32_e32 v16, v137
	v_mov_b32_e32 v17, v137
	v_mov_b32_e32 v18, v137
	v_mov_b32_e32 v19, v137
	v_mov_b32_e32 v80, v137
	v_mov_b32_e32 v81, v137
	v_mov_b32_e32 v82, v137
	v_mov_b32_e32 v83, v137
	v_mov_b32_e32 v84, v137
	v_mov_b32_e32 v85, v137
	v_mov_b32_e32 v86, v137
	v_mov_b32_e32 v87, v137
	v_mov_b32_e32 v20, v137
	v_mov_b32_e32 v21, v137
	v_mov_b32_e32 v22, v137
	v_mov_b32_e32 v23, v137
	v_mov_b32_e32 v24, v137
	v_mov_b32_e32 v25, v137
	v_mov_b32_e32 v26, v137
	v_mov_b32_e32 v27, v137
	v_mov_b32_e32 v88, v137
	v_mov_b32_e32 v89, v137
	v_mov_b32_e32 v90, v137
	v_mov_b32_e32 v91, v137
	v_mov_b32_e32 v92, v137
	v_mov_b32_e32 v93, v137
	v_mov_b32_e32 v94, v137
	v_mov_b32_e32 v95, v137
	v_mov_b32_e32 v28, v137
	v_mov_b32_e32 v29, v137
	v_mov_b32_e32 v30, v137
	v_mov_b32_e32 v31, v137
	v_mov_b32_e32 v32, v137
	v_mov_b32_e32 v33, v137
	v_mov_b32_e32 v34, v137
	v_mov_b32_e32 v35, v137
	v_mov_b32_e32 v96, v137
	v_mov_b32_e32 v97, v137
	v_mov_b32_e32 v98, v137
	v_mov_b32_e32 v99, v137
	v_mov_b32_e32 v100, v137
	v_mov_b32_e32 v101, v137
	v_mov_b32_e32 v102, v137
	v_mov_b32_e32 v103, v137
	v_mov_b32_e32 v36, v137
	v_mov_b32_e32 v37, v137
	v_mov_b32_e32 v38, v137
	v_mov_b32_e32 v39, v137
	v_mov_b32_e32 v40, v137
	v_mov_b32_e32 v41, v137
	v_mov_b32_e32 v42, v137
	v_mov_b32_e32 v43, v137
	v_mov_b32_e32 v104, v137
	v_mov_b32_e32 v105, v137
	v_mov_b32_e32 v106, v137
	v_mov_b32_e32 v107, v137
	v_mov_b32_e32 v108, v137
	v_mov_b32_e32 v109, v137
	v_mov_b32_e32 v110, v137
	v_mov_b32_e32 v111, v137
	v_mov_b32_e32 v44, v137
	v_mov_b32_e32 v45, v137
	v_mov_b32_e32 v46, v137
	v_mov_b32_e32 v47, v137
	v_mov_b32_e32 v48, v137
	v_mov_b32_e32 v49, v137
	v_mov_b32_e32 v50, v137
	v_mov_b32_e32 v51, v137
	v_mov_b32_e32 v112, v137
	v_mov_b32_e32 v113, v137
	v_mov_b32_e32 v114, v137
	v_mov_b32_e32 v115, v137
	v_mov_b32_e32 v116, v137
	v_mov_b32_e32 v117, v137
	v_mov_b32_e32 v118, v137
	v_mov_b32_e32 v119, v137
	v_mov_b32_e32 v52, v137
	v_mov_b32_e32 v53, v137
	v_mov_b32_e32 v54, v137
	v_mov_b32_e32 v55, v137
	v_mov_b32_e32 v60, v137
	v_mov_b32_e32 v61, v137
	v_mov_b32_e32 v62, v137
	v_mov_b32_e32 v63, v137
	v_mov_b32_e32 v120, v137
	v_mov_b32_e32 v121, v137
	v_mov_b32_e32 v122, v137
	v_mov_b32_e32 v123, v137
	v_mov_b32_e32 v124, v137
	v_mov_b32_e32 v125, v137
	v_mov_b32_e32 v126, v137
	v_mov_b32_e32 v127, v137
	s_waitcnt vmcnt(0) lgkmcnt(0)
	s_barrier
	s_mov_b32 s17, 0x10000
	s_and_b32 s17, s16, 0x10000
	s_xor_b32 s33, s17, 0x10000
	s_add_i32 s33, s5, s33
	s_add_i32 s34, s33, 0x8000
	s_mov_b32 m0, s33
	v_lshl_add_u64 v[254:255], v[162:163], 0, s[0:1]
	global_load_lds_dwordx4 v[254:255], off
	s_add_i32 m0, s33, 0x2000
	v_lshl_add_u64 v[254:255], v[164:165], 0, s[0:1]
	global_load_lds_dwordx4 v[254:255], off
	s_add_i32 m0, s33, 0x4000
	v_lshl_add_u64 v[254:255], v[166:167], 0, s[0:1]
	global_load_lds_dwordx4 v[254:255], off
	s_add_i32 m0, s33, 0x6000
	v_lshl_add_u64 v[254:255], v[168:169], 0, s[0:1]
	global_load_lds_dwordx4 v[254:255], off
	s_mov_b32 m0, s34
	v_lshl_add_u64 v[254:255], v[170:171], 0, s[0:1]
	global_load_lds_dwordx4 v[254:255], off
	s_add_i32 m0, s33, 0xa000
	v_lshl_add_u64 v[254:255], v[172:173], 0, s[0:1]
	global_load_lds_dwordx4 v[254:255], off
	s_add_i32 m0, s33, 0xc000
	v_lshl_add_u64 v[254:255], v[174:175], 0, s[0:1]
	global_load_lds_dwordx4 v[254:255], off
	s_add_i32 m0, s33, 0xe000
	v_lshl_add_u64 v[254:255], v[176:177], 0, s[0:1]
	global_load_lds_dwordx4 v[254:255], off
	v_add3_u32 v253, s17, v153, v129
	ds_read_b128 v[214:217], v253 offset:0x1000
	ds_read_b128 v[218:221], v253 offset:0x1800
	ds_read_b128 v[206:209], v253 offset:0
	v_add3_u32 v253, s17, v155, v129
	ds_read_b128 v[178:181], v253 offset:0
	v_add3_u32 v253, s17, v153, v129
	ds_read_b128 v[210:213], v253 offset:0x800
	v_add3_u32 v253, s17, v155, v129
	ds_read_b128 v[182:185], v253 offset:0x800
	ds_read_b128 v[198:201], v253 offset:0x1000
	ds_read_b128 v[202:205], v253 offset:0x1800
	.p2align 6

.LBB0_742:
	s_ashr_i32 s4, s17, 31
	s_lshr_b32 s4, s4, 26
	s_add_i32 s4, s17, s4
	v_readfirstlane_b32 s9, v128
	s_ashr_i32 s10, s4, 6
	s_andn2_b32 s4, s4, 63
	s_lshr_b32 s11, s9, 1
	s_sub_i32 s8, s17, s4
	s_and_b32 s11, s11, 0x1ffff80
	s_lshl_b32 s4, s8, 19
	v_or_b32_e32 v8, s11, v189
	s_and_b32 s11, s9, 0xc0
	s_lshl_b32 s9, s9, 4
	v_add_u32_e32 v0, s4, v134
	v_lshlrev_b32_e32 v141, 7, v8
	v_or_b32_e32 v8, s11, v189
	s_and_b32 s9, s9, 0x7ffffc00
	v_add_u32_e32 v1, s4, v138
	v_lshl_or_b32 v143, v8, 7, v139
	v_and_b32_e32 v8, 0xfffff870, v0
	s_mov_b32 m0, s9
	v_add_u32_e32 v2, s4, v140
	global_load_lds_dwordx4 v8, s[86:87]
	v_and_b32_e32 v1, 0xfffff870, v1
	s_add_i32 m0, s9, 0x2000
	s_lshl_b32 s5, s10, 19
	v_add_u32_e32 v3, s4, v142
	global_load_lds_dwordx4 v1, s[86:87]
	v_and_b32_e32 v1, 0xfffff870, v2
	s_add_i32 m0, s9, 0x4000
	v_add_u32_e32 v4, s5, v144
	s_add_i32 s11, s9, 0x8000
	global_load_lds_dwordx4 v1, s[86:87]
	v_and_b32_e32 v1, 0xfffff870, v3
	s_add_i32 m0, s9, 0x6000
	v_add_u32_e32 v5, s5, v146
	global_load_lds_dwordx4 v1, s[86:87]
	v_and_b32_e32 v1, 0xfffff870, v4
	s_mov_b32 m0, s11
	v_add_u32_e32 v6, s5, v148
	global_load_lds_dwordx4 v1, s[86:87]
	v_and_b32_e32 v1, 0xfffff870, v5
	s_add_i32 m0, s9, 0xa000
	v_add_u32_e32 v7, s5, v150
	global_load_lds_dwordx4 v1, s[86:87]
	v_and_b32_e32 v1, 0xfffff870, v6
	s_add_i32 m0, s9, 0xc000
	v_and_b32_e32 v136, -16, v0
	global_load_lds_dwordx4 v1, s[86:87]
	v_and_b32_e32 v1, 0xfffff870, v7
	s_add_i32 m0, s9, 0xe000
	v_add_u32_e32 v0, s4, v152
	global_load_lds_dwordx4 v1, s[86:87]
	v_lshl_add_u64 v[162:163], s[6:7], 0, v[136:137]
	v_and_b32_e32 v136, -16, v0
	v_add_u32_e32 v0, s4, v154
	v_lshl_add_u64 v[164:165], s[6:7], 0, v[136:137]
	v_and_b32_e32 v136, -16, v0
	v_add_u32_e32 v0, s4, v156
	v_lshl_add_u64 v[166:167], s[6:7], 0, v[136:137]
	v_and_b32_e32 v136, -16, v0
	v_lshl_add_u64 v[168:169], s[6:7], 0, v[136:137]
	v_and_b32_e32 v136, -16, v4
	v_add_u32_e32 v0, s5, v158
	v_lshl_add_u64 v[170:171], s[6:7], 0, v[136:137]
	v_and_b32_e32 v136, -16, v0
	s_waitcnt vmcnt(0)
	v_lshl_add_u64 v[172:173], s[6:7], 0, v[136:137]
	v_and_b32_e32 v136, -16, v6
	v_add_u32_e32 v0, s5, v160
	v_lshl_add_u64 v[174:175], s[6:7], 0, v[136:137]
	v_and_b32_e32 v136, -16, v0
	v_lshl_add_u64 v[176:177], s[6:7], 0, v[136:137]
	s_mov_b64 s[4:5], 0
	s_mov_b32 s11, 0
	s_mov_b32 s18, 0
	v_mov_b32_e32 v56, 0
	v_mov_b32_e32 v57, v137
	v_mov_b32_e32 v58, v137
	v_mov_b32_e32 v59, v137
	v_mov_b32_e32 v52, 0
	v_mov_b32_e32 v53, v137
	v_mov_b32_e32 v54, v137
	v_mov_b32_e32 v55, v137
	v_mov_b32_e32 v64, 0
	v_mov_b32_e32 v65, v137
	v_mov_b32_e32 v66, v137
	v_mov_b32_e32 v67, v137
	v_mov_b32_e32 v68, 0
	v_mov_b32_e32 v69, v137
	v_mov_b32_e32 v70, v137
	v_mov_b32_e32 v71, v137
	v_mov_b32_e32 v0, 0
	v_mov_b32_e32 v1, v137
	v_mov_b32_e32 v2, v137
	v_mov_b32_e32 v3, v137
	v_mov_b32_e32 v4, 0
	v_mov_b32_e32 v5, v137
	v_mov_b32_e32 v6, v137
	v_mov_b32_e32 v7, v137
	v_mov_b32_e32 v72, 0
	v_mov_b32_e32 v73, v137
	v_mov_b32_e32 v74, v137
	v_mov_b32_e32 v75, v137
	v_mov_b32_e32 v76, 0
	v_mov_b32_e32 v77, v137
	v_mov_b32_e32 v78, v137
	v_mov_b32_e32 v79, v137
	v_mov_b32_e32 v8, 0
	v_mov_b32_e32 v9, v137
	v_mov_b32_e32 v10, v137
	v_mov_b32_e32 v11, v137
	v_mov_b32_e32 v12, 0
	v_mov_b32_e32 v13, v137
	v_mov_b32_e32 v14, v137
	v_mov_b32_e32 v15, v137
	v_mov_b32_e32 v80, 0
	v_mov_b32_e32 v81, v137
	v_mov_b32_e32 v82, v137
	v_mov_b32_e32 v83, v137
	v_mov_b32_e32 v84, 0
	v_mov_b32_e32 v85, v137
	v_mov_b32_e32 v86, v137
	v_mov_b32_e32 v87, v137
	v_mov_b32_e32 v16, 0
	v_mov_b32_e32 v17, v137
	v_mov_b32_e32 v18, v137
	v_mov_b32_e32 v19, v137
	v_mov_b32_e32 v20, 0
	v_mov_b32_e32 v21, v137
	v_mov_b32_e32 v22, v137
	v_mov_b32_e32 v23, v137
	v_mov_b32_e32 v88, 0
	v_mov_b32_e32 v89, v137
	v_mov_b32_e32 v90, v137
	v_mov_b32_e32 v91, v137
	v_mov_b32_e32 v92, 0
	v_mov_b32_e32 v93, v137
	v_mov_b32_e32 v94, v137
	v_mov_b32_e32 v95, v137
	v_mov_b32_e32 v24, 0
	v_mov_b32_e32 v25, v137
	v_mov_b32_e32 v26, v137
	v_mov_b32_e32 v27, v137
	v_mov_b32_e32 v28, 0
	v_mov_b32_e32 v29, v137
	v_mov_b32_e32 v30, v137
	v_mov_b32_e32 v31, v137
	s_waitcnt vmcnt(0)
	v_mov_b32_e32 v96, 0
	v_mov_b32_e32 v97, v137
	v_mov_b32_e32 v98, v137
	v_mov_b32_e32 v99, v137
	v_mov_b32_e32 v100, 0
	v_mov_b32_e32 v101, v137
	v_mov_b32_e32 v102, v137
	v_mov_b32_e32 v103, v137
	v_mov_b32_e32 v32, 0
	v_mov_b32_e32 v33, v137
	v_mov_b32_e32 v34, v137
	v_mov_b32_e32 v35, v137
	v_mov_b32_e32 v36, 0
	v_mov_b32_e32 v37, v137
	v_mov_b32_e32 v38, v137
	v_mov_b32_e32 v39, v137
	v_mov_b32_e32 v104, 0
	v_mov_b32_e32 v105, v137
	v_mov_b32_e32 v106, v137
	v_mov_b32_e32 v107, v137
	v_mov_b32_e32 v108, 0
	v_mov_b32_e32 v109, v137
	v_mov_b32_e32 v110, v137
	v_mov_b32_e32 v111, v137
	v_mov_b32_e32 v40, 0
	v_mov_b32_e32 v41, v137
	v_mov_b32_e32 v42, v137
	v_mov_b32_e32 v43, v137
	v_mov_b32_e32 v44, 0
	v_mov_b32_e32 v45, v137
	v_mov_b32_e32 v46, v137
	v_mov_b32_e32 v47, v137
	v_mov_b32_e32 v112, 0
	v_mov_b32_e32 v113, v137
	v_mov_b32_e32 v114, v137
	v_mov_b32_e32 v115, v137
	v_mov_b32_e32 v116, 0
	v_mov_b32_e32 v117, v137
	v_mov_b32_e32 v118, v137
	v_mov_b32_e32 v119, v137
	v_mov_b32_e32 v48, 0
	v_mov_b32_e32 v49, v137
	v_mov_b32_e32 v50, v137
	v_mov_b32_e32 v51, v137
	v_mov_b32_e32 v60, 0
	v_mov_b32_e32 v61, v137
	v_mov_b32_e32 v62, v137
	v_mov_b32_e32 v63, v137
	v_mov_b32_e32 v120, 0
	v_mov_b32_e32 v121, v137
	v_mov_b32_e32 v122, v137
	v_mov_b32_e32 v123, v137
	v_mov_b32_e32 v124, 0
	v_mov_b32_e32 v125, v137
	v_mov_b32_e32 v126, v137
	v_mov_b32_e32 v127, v137
	s_waitcnt lgkmcnt(0)
	s_barrier
	s_and_b32 s19, s11, 0x10000
	s_xor_b32 s24, s19, 0x10000
	s_add_i32 s24, s9, s24
	s_add_i32 s25, s24, 0x8000
	s_mov_b32 m0, s24
	v_lshl_add_u64 v[254:255], v[162:163], 0, s[4:5]
	global_load_lds_dwordx4 v[254:255], off
	s_add_i32 m0, s24, 0x2000
	v_lshl_add_u64 v[254:255], v[164:165], 0, s[4:5]
	global_load_lds_dwordx4 v[254:255], off
	s_add_i32 m0, s24, 0x4000
	v_lshl_add_u64 v[254:255], v[166:167], 0, s[4:5]
	global_load_lds_dwordx4 v[254:255], off
	s_add_i32 m0, s24, 0x6000
	v_lshl_add_u64 v[254:255], v[168:169], 0, s[4:5]
	global_load_lds_dwordx4 v[254:255], off
	s_mov_b32 m0, s25
	v_lshl_add_u64 v[254:255], v[170:171], 0, s[4:5]
	global_load_lds_dwordx4 v[254:255], off
	s_add_i32 m0, s24, 0xa000
	v_lshl_add_u64 v[254:255], v[172:173], 0, s[4:5]
	global_load_lds_dwordx4 v[254:255], off
	s_add_i32 m0, s24, 0xc000
	v_lshl_add_u64 v[254:255], v[174:175], 0, s[4:5]
	global_load_lds_dwordx4 v[254:255], off
	s_add_i32 m0, s24, 0xe000
	v_lshl_add_u64 v[254:255], v[176:177], 0, s[4:5]
	global_load_lds_dwordx4 v[254:255], off
	v_add3_u32 v253, s19, v141, v129
	ds_read_b128 v[214:217], v253 offset:0x1000
	ds_read_b128 v[218:221], v253 offset:0x1800
	ds_read_b128 v[206:209], v253 offset:0
	v_add3_u32 v253, s19, v143, v129
	ds_read_b128 v[178:181], v253 offset:0
	v_add3_u32 v253, s19, v141, v129
	ds_read_b128 v[210:213], v253 offset:0x800
	v_add3_u32 v253, s19, v143, v129
	ds_read_b128 v[182:185], v253 offset:0x800
	ds_read_b128 v[198:201], v253 offset:0x1000
	ds_read_b128 v[202:205], v253 offset:0x1800
	.p2align 6

.LBB0_1004:
	s_waitcnt vmcnt(2)
	v_add_u32_e32 v6, s5, v139
	v_cmp_lt_i32_e32 vcc, s13, v6
	s_and_saveexec_b64 s[0:1], vcc
	s_xor_b64 s[0:1], exec, s[0:1]
	v_add_u32_e32 v4, 0xffffff78, v6
	v_mul_hi_u32 v3, v4, s12
	v_lshrrev_b32_e32 v5, 1, v3
	v_lshl_add_u32 v3, v5, 8, v149
	v_lshl_add_u32 v5, v5, 1, v5
	v_sub_u32_e32 v4, v4, v5
	s_or_saveexec_b64 s[0:1], s[0:1]
	v_mov_b32_e32 v5, 0x100
	s_xor_b64 exec, exec, s[0:1]
	v_mul_hi_i32 v3, v6, s14
	v_lshrrev_b32_e32 v4, 31, v3
	v_ashrrev_i32_e32 v3, 3, v3
	v_add_u32_e32 v4, v3, v4
	v_lshlrev_b32_e32 v3, 11, v4
	v_lshl_add_u32 v4, v4, 4, v4
	v_sub_u32_e32 v4, v6, v4
	v_mov_b32_e32 v5, 0x800
	s_or_b64 exec, exec, s[0:1]
	s_mul_i32 s0, s27, 0x7e
	v_add_u32_e32 v8, s0, v129
	v_add_u32_e32 v6, s25, v8
	v_lshl_add_u32 v9, v6, 11, v136
	v_mad_u64_u32 v[6:7], s[0:1], v1, s15, v[138:139]
	s_mul_i32 s0, s7, 0x7e
	v_add_u32_e32 v0, v6, v0
	v_add_u32_e32 v10, s0, v129
	v_lshl_add_u32 v7, v0, 11, v140
	v_add_u32_e32 v0, s6, v10
	v_lshl_add_u32 v11, v0, 11, v136
	v_mad_u64_u32 v[0:1], s[0:1], v4, s15, v[142:143]
	v_cmp_gt_u32_e32 vcc, s24, v10
	v_add_u32_e32 v1, v0, v3
	v_readfirstlane_b32 s0, v128
	v_cndmask_b32_e32 v3, v145, v11, vcc
	v_cmp_lt_u32_e32 vcc, v6, v2
	s_lshr_b32 s1, s0, 1
	v_lshl_add_u32 v1, v1, 11, v144
	v_cndmask_b32_e32 v2, v145, v7, vcc
	v_cmp_gt_u32_e32 vcc, s26, v8
	v_subrev_u32_e32 v134, s86, v3
	s_and_b32 s1, s1, 0x1ffff80
	v_cndmask_b32_e32 v3, v145, v9, vcc
	v_cmp_lt_u32_e32 vcc, v0, v5
	v_subrev_u32_e32 v2, s86, v2
	s_lshl_b32 s7, s4, 19
	v_cndmask_b32_e32 v0, v145, v1, vcc
	v_or_b32_e32 v1, s1, v189
	s_and_b32 s1, s0, 0xc0
	s_lshl_b32 s0, s0, 4
	s_and_b32 s6, s0, 0x7ffffc00
	s_mov_b32 m0, s6
	v_subrev_u32_e32 v4, s86, v3
	global_load_lds_dwordx4 v134, s[86:87]
	s_add_i32 m0, s6, 0x2000
	v_subrev_u32_e32 v0, s86, v0
	global_load_lds_dwordx4 v2, s[86:87]
	s_add_i32 m0, s6, 0x4000
	v_add_u32_e32 v6, s7, v146
	s_add_i32 s0, s6, 0x8000
	global_load_lds_dwordx4 v4, s[86:87]
	s_add_i32 m0, s6, 0x6000
	v_add_u32_e32 v8, s7, v148
	global_load_lds_dwordx4 v0, s[86:87]
	v_and_b32_e32 v6, 0xfffff870, v6
	s_mov_b32 m0, s0
	v_add_u32_e32 v9, s7, v150
	global_load_lds_dwordx4 v6, s[86:87]
	v_and_b32_e32 v8, 0xfffff870, v8
	s_add_i32 m0, s6, 0xa000
	v_add_u32_e32 v10, s7, v152
	global_load_lds_dwordx4 v8, s[86:87]
	v_and_b32_e32 v8, 0xfffff870, v9
	s_add_i32 m0, s6, 0xc000
	v_and_b32_e32 v10, 0xfffff870, v10
	global_load_lds_dwordx4 v8, s[86:87]
	s_add_i32 m0, s6, 0xe000
	v_lshlrev_b32_e32 v155, 7, v1
	global_load_lds_dwordx4 v10, s[86:87]
	v_or_b32_e32 v1, s1, v189
	v_lshl_or_b32 v172, v1, 7, v147
	v_mov_b32_e32 v1, v135
	s_waitcnt vmcnt(0)
	v_lshl_add_u64 v[162:163], s[56:57], 0, v[0:1]
	v_add_u32_e32 v0, s7, v154
	v_mov_b32_e32 v3, v135
	v_mov_b32_e32 v5, v135
	v_mov_b32_e32 v7, v135
	v_mov_b32_e32 v9, v135
	v_mov_b32_e32 v11, v135
	v_lshl_add_u64 v[156:157], s[56:57], 0, v[134:135]
	v_and_b32_e32 v134, -16, v0
	v_mov_b32_e32 v52, 0
	v_lshl_add_u64 v[158:159], s[56:57], 0, v[2:3]
	v_lshl_add_u64 v[160:161], s[56:57], 0, v[4:5]
	v_lshl_add_u64 v[164:165], s[56:57], 0, v[6:7]
	v_lshl_add_u64 v[166:167], s[56:57], 0, v[134:135]
	v_lshl_add_u64 v[168:169], s[56:57], 0, v[8:9]
	v_lshl_add_u64 v[170:171], s[56:57], 0, v[10:11]
	s_mov_b32 s7, 0
	s_mov_b64 s[0:1], 0
	v_mov_b32_e32 v53, v52
	v_mov_b32_e32 v54, v52
	v_mov_b32_e32 v55, v52
	v_mov_b32_e32 v0, v52
	v_mov_b32_e32 v1, v52
	v_mov_b32_e32 v2, v52
	v_mov_b32_e32 v3, v52
	v_mov_b32_e32 v64, v52
	v_mov_b32_e32 v65, v52
	v_mov_b32_e32 v66, v52
	v_mov_b32_e32 v67, v52
	v_mov_b32_e32 v68, v52
	v_mov_b32_e32 v69, v52
	v_mov_b32_e32 v70, v52
	v_mov_b32_e32 v71, v52
	v_mov_b32_e32 v4, v52
	v_mov_b32_e32 v5, v52
	v_mov_b32_e32 v6, v52
	v_mov_b32_e32 v7, v52
	v_mov_b32_e32 v8, v52
	v_mov_b32_e32 v9, v52
	v_mov_b32_e32 v10, v52
	v_mov_b32_e32 v11, v52
	v_mov_b32_e32 v72, v52
	v_mov_b32_e32 v73, v52
	v_mov_b32_e32 v74, v52
	v_mov_b32_e32 v75, v52
	v_mov_b32_e32 v76, v52
	v_mov_b32_e32 v77, v52
	v_mov_b32_e32 v78, v52
	v_mov_b32_e32 v79, v52
	s_waitcnt vmcnt(0)
	v_mov_b32_e32 v12, v52
	v_mov_b32_e32 v13, v52
	v_mov_b32_e32 v14, v52
	v_mov_b32_e32 v15, v52
	v_mov_b32_e32 v16, v52
	v_mov_b32_e32 v17, v52
	v_mov_b32_e32 v18, v52
	v_mov_b32_e32 v19, v52
	v_mov_b32_e32 v80, v52
	v_mov_b32_e32 v81, v52
	v_mov_b32_e32 v82, v52
	v_mov_b32_e32 v83, v52
	v_mov_b32_e32 v84, v52
	v_mov_b32_e32 v85, v52
	v_mov_b32_e32 v86, v52
	v_mov_b32_e32 v87, v52
	v_mov_b32_e32 v20, v52
	v_mov_b32_e32 v21, v52
	v_mov_b32_e32 v22, v52
	v_mov_b32_e32 v23, v52
	v_mov_b32_e32 v24, v52
	v_mov_b32_e32 v25, v52
	v_mov_b32_e32 v26, v52
	v_mov_b32_e32 v27, v52
	v_mov_b32_e32 v88, v52
	v_mov_b32_e32 v89, v52
	v_mov_b32_e32 v90, v52
	v_mov_b32_e32 v91, v52
	v_mov_b32_e32 v92, v52
	v_mov_b32_e32 v93, v52
	v_mov_b32_e32 v94, v52
	v_mov_b32_e32 v95, v52
	v_mov_b32_e32 v28, v52
	v_mov_b32_e32 v29, v52
	v_mov_b32_e32 v30, v52
	v_mov_b32_e32 v31, v52
	v_mov_b32_e32 v32, v52
	v_mov_b32_e32 v33, v52
	v_mov_b32_e32 v34, v52
	v_mov_b32_e32 v35, v52
	s_waitcnt vmcnt(0)
	v_mov_b32_e32 v96, v52
	v_mov_b32_e32 v97, v52
	v_mov_b32_e32 v98, v52
	v_mov_b32_e32 v99, v52
	v_mov_b32_e32 v100, v52
	v_mov_b32_e32 v101, v52
	v_mov_b32_e32 v102, v52
	v_mov_b32_e32 v103, v52
	v_mov_b32_e32 v36, v52
	v_mov_b32_e32 v37, v52
	v_mov_b32_e32 v38, v52
	v_mov_b32_e32 v39, v52
	v_mov_b32_e32 v40, v52
	v_mov_b32_e32 v41, v52
	v_mov_b32_e32 v42, v52
	v_mov_b32_e32 v43, v52
	v_mov_b32_e32 v104, v52
	v_mov_b32_e32 v105, v52
	v_mov_b32_e32 v106, v52
	v_mov_b32_e32 v107, v52
	v_mov_b32_e32 v108, v52
	v_mov_b32_e32 v109, v52
	v_mov_b32_e32 v110, v52
	v_mov_b32_e32 v111, v52
	v_mov_b32_e32 v44, v52
	v_mov_b32_e32 v45, v52
	v_mov_b32_e32 v46, v52
	v_mov_b32_e32 v47, v52
	v_mov_b32_e32 v48, v52
	v_mov_b32_e32 v49, v52
	v_mov_b32_e32 v50, v52
	v_mov_b32_e32 v51, v52
	v_mov_b32_e32 v112, v52
	v_mov_b32_e32 v113, v52
	v_mov_b32_e32 v114, v52
	v_mov_b32_e32 v115, v52
	v_mov_b32_e32 v116, v52
	v_mov_b32_e32 v117, v52
	v_mov_b32_e32 v118, v52
	v_mov_b32_e32 v119, v52
	v_mov_b32_e32 v56, v52
	v_mov_b32_e32 v57, v52
	v_mov_b32_e32 v58, v52
	v_mov_b32_e32 v59, v52
	v_mov_b32_e32 v60, v52
	v_mov_b32_e32 v61, v52
	v_mov_b32_e32 v62, v52
	v_mov_b32_e32 v63, v52
	v_mov_b32_e32 v120, v52
	v_mov_b32_e32 v121, v52
	v_mov_b32_e32 v122, v52
	v_mov_b32_e32 v123, v52
	v_mov_b32_e32 v124, v52
	v_mov_b32_e32 v125, v52
	v_mov_b32_e32 v126, v52
	v_mov_b32_e32 v127, v52
	s_waitcnt lgkmcnt(0)
	s_barrier
	s_mov_b32 s24, 0x10000
	s_and_b32 s24, s7, 0x10000
	s_xor_b32 s25, s24, 0x10000
	s_add_i32 s25, s6, s25
	s_add_i32 s26, s25, 0x8000
	s_mov_b32 m0, s25
	v_lshl_add_u64 v[254:255], v[156:157], 0, s[0:1]
	global_load_lds_dwordx4 v[254:255], off
	s_add_i32 m0, s25, 0x2000
	v_lshl_add_u64 v[254:255], v[158:159], 0, s[0:1]
	global_load_lds_dwordx4 v[254:255], off
	s_add_i32 m0, s25, 0x4000
	v_lshl_add_u64 v[254:255], v[160:161], 0, s[0:1]
	global_load_lds_dwordx4 v[254:255], off
	s_add_i32 m0, s25, 0x6000
	v_lshl_add_u64 v[254:255], v[162:163], 0, s[0:1]
	global_load_lds_dwordx4 v[254:255], off
	s_mov_b32 m0, s26
	v_lshl_add_u64 v[254:255], v[164:165], 0, s[0:1]
	global_load_lds_dwordx4 v[254:255], off
	s_add_i32 m0, s25, 0xa000
	v_lshl_add_u64 v[254:255], v[166:167], 0, s[0:1]
	global_load_lds_dwordx4 v[254:255], off
	s_add_i32 m0, s25, 0xc000
	v_lshl_add_u64 v[254:255], v[168:169], 0, s[0:1]
	global_load_lds_dwordx4 v[254:255], off
	s_add_i32 m0, s25, 0xe000
	v_lshl_add_u64 v[254:255], v[170:171], 0, s[0:1]
	global_load_lds_dwordx4 v[254:255], off
	v_add3_u32 v253, s24, v155, v141
	ds_read_b128 v[210:213], v253 offset:0x1000
	ds_read_b128 v[214:217], v253 offset:0x1800
	ds_read_b128 v[202:205], v253 offset:0
	v_add3_u32 v253, s24, v172, v141
	ds_read_b128 v[174:177], v253 offset:0
	v_add3_u32 v253, s24, v155, v141
	ds_read_b128 v[206:209], v253 offset:0x800
	v_add3_u32 v253, s24, v172, v141
	ds_read_b128 v[178:181], v253 offset:0x800
	ds_read_b128 v[182:185], v253 offset:0x1000
	ds_read_b128 v[198:201], v253 offset:0x1800
	.p2align 6

.LBB0_1191:
	s_ashr_i32 s6, s17, 31
	s_lshr_b32 s6, s6, 26
	s_add_i32 s6, s17, s6
	s_ashr_i32 s12, s6, 6
	s_andn2_b32 s6, s6, 63
	s_sub_i32 s10, s17, s6
	s_mul_i32 s6, s10, 0xb0000
	v_readfirstlane_b32 s11, v128
	s_lshl_b32 s13, s6, 1
	v_or_b32_e32 v3, s6, v134
	s_lshr_b32 s6, s11, 1
	s_and_b32 s6, s6, 0x1ffff80
	v_lshl_add_u32 v4, v3, 1, v144
	v_or_b32_e32 v3, s6, v189
	s_and_b32 s6, s11, 0xc0
	v_lshlrev_b32_e32 v141, 7, v3
	v_or_b32_e32 v3, s6, v189
	s_lshl_b32 s6, s11, 4
	v_add_u32_e32 v0, s13, v138
	s_and_b32 s11, s6, 0x7ffffc00
	v_add_u32_e32 v1, s13, v140
	v_and_b32_e32 v136, 0xfffffe70, v0
	s_mov_b32 m0, s11
	v_add_u32_e32 v2, s13, v142
	global_load_lds_dwordx4 v136, s[86:87]
	v_and_b32_e32 v0, 0xfffffe70, v1
	s_add_i32 m0, s11, 0x2000
	s_mul_i32 s7, s12, 0x160000
	global_load_lds_dwordx4 v0, s[86:87]
	v_and_b32_e32 v2, 0xfffffe70, v2
	s_add_i32 m0, s11, 0x4000
	v_add_u32_e32 v6, s7, v146
	s_add_i32 s6, s11, 0x8000
	global_load_lds_dwordx4 v2, s[86:87]
	v_and_b32_e32 v4, 0xfffffe70, v4
	s_add_i32 m0, s11, 0x6000
	v_add_u32_e32 v8, s7, v148
	global_load_lds_dwordx4 v4, s[86:87]
	v_and_b32_e32 v6, 0xfffffe70, v6
	s_mov_b32 m0, s6
	v_add_u32_e32 v10, s7, v150
	global_load_lds_dwordx4 v6, s[86:87]
	v_and_b32_e32 v8, 0xfffffe70, v8
	s_add_i32 m0, s11, 0xa000
	s_waitcnt vmcnt(0)
	v_add_u32_e32 v12, s7, v152
	global_load_lds_dwordx4 v8, s[86:87]
	v_and_b32_e32 v10, 0xfffffe70, v10
	s_add_i32 m0, s11, 0xc000
	v_and_b32_e32 v12, 0xfffffe70, v12
	global_load_lds_dwordx4 v10, s[86:87]
	s_add_i32 m0, s11, 0xe000
	v_lshl_or_b32 v143, v3, 7, v139
	global_load_lds_dwordx4 v12, s[86:87]
	s_waitcnt vmcnt(0)
	v_mov_b32_e32 v1, v137
	v_mov_b32_e32 v3, v137
	v_mov_b32_e32 v5, v137
	v_mov_b32_e32 v7, v137
	v_mov_b32_e32 v9, v137
	v_mov_b32_e32 v11, v137
	v_mov_b32_e32 v13, v137
	v_lshl_add_u64 v[154:155], s[8:9], 0, v[136:137]
	v_lshl_add_u64 v[156:157], s[8:9], 0, v[0:1]
	v_lshl_add_u64 v[158:159], s[8:9], 0, v[2:3]
	v_lshl_add_u64 v[160:161], s[8:9], 0, v[4:5]
	v_lshl_add_u64 v[162:163], s[8:9], 0, v[6:7]
	v_lshl_add_u64 v[164:165], s[8:9], 0, v[8:9]
	v_lshl_add_u64 v[166:167], s[8:9], 0, v[10:11]
	v_lshl_add_u64 v[168:169], s[8:9], 0, v[12:13]
	s_mov_b64 s[6:7], 0
	s_mov_b32 s13, 0
	s_mov_b32 s20, 0
	v_mov_b32_e32 v56, 0
	v_mov_b32_e32 v57, v137
	v_mov_b32_e32 v58, v137
	v_mov_b32_e32 v59, v137
	v_mov_b32_e32 v52, 0
	v_mov_b32_e32 v53, v137
	v_mov_b32_e32 v54, v137
	v_mov_b32_e32 v55, v137
	v_mov_b32_e32 v64, 0
	v_mov_b32_e32 v65, v137
	v_mov_b32_e32 v66, v137
	v_mov_b32_e32 v67, v137
	v_mov_b32_e32 v68, 0
	v_mov_b32_e32 v69, v137
	v_mov_b32_e32 v70, v137
	v_mov_b32_e32 v71, v137
	v_mov_b32_e32 v0, 0
	v_mov_b32_e32 v2, v137
	v_mov_b32_e32 v4, 0
	v_mov_b32_e32 v6, v137
	v_mov_b32_e32 v72, 0
	v_mov_b32_e32 v73, v137
	v_mov_b32_e32 v74, v137
	v_mov_b32_e32 v75, v137
	v_mov_b32_e32 v76, 0
	v_mov_b32_e32 v77, v137
	v_mov_b32_e32 v78, v137
	v_mov_b32_e32 v79, v137
	v_mov_b32_e32 v8, 0
	v_mov_b32_e32 v10, v137
	v_mov_b32_e32 v12, 0
	v_mov_b32_e32 v14, v137
	v_mov_b32_e32 v15, v137
	v_mov_b32_e32 v80, 0
	v_mov_b32_e32 v81, v137
	v_mov_b32_e32 v82, v137
	v_mov_b32_e32 v83, v137
	v_mov_b32_e32 v84, 0
	v_mov_b32_e32 v85, v137
	v_mov_b32_e32 v86, v137
	v_mov_b32_e32 v87, v137
	v_mov_b32_e32 v16, 0
	v_mov_b32_e32 v17, v137
	v_mov_b32_e32 v18, v137
	v_mov_b32_e32 v19, v137
	v_mov_b32_e32 v20, 0
	v_mov_b32_e32 v21, v137
	v_mov_b32_e32 v22, v137
	v_mov_b32_e32 v23, v137
	v_mov_b32_e32 v88, 0
	v_mov_b32_e32 v89, v137
	v_mov_b32_e32 v90, v137
	v_mov_b32_e32 v91, v137
	v_mov_b32_e32 v92, 0
	v_mov_b32_e32 v93, v137
	v_mov_b32_e32 v94, v137
	v_mov_b32_e32 v95, v137
	v_mov_b32_e32 v24, 0
	v_mov_b32_e32 v25, v137
	v_mov_b32_e32 v26, v137
	v_mov_b32_e32 v27, v137
	v_mov_b32_e32 v28, 0
	v_mov_b32_e32 v29, v137
	v_mov_b32_e32 v30, v137
	v_mov_b32_e32 v31, v137
	v_mov_b32_e32 v96, 0
	v_mov_b32_e32 v97, v137
	v_mov_b32_e32 v98, v137
	v_mov_b32_e32 v99, v137
	v_mov_b32_e32 v100, 0
	v_mov_b32_e32 v101, v137
	v_mov_b32_e32 v102, v137
	v_mov_b32_e32 v103, v137
	v_mov_b32_e32 v32, 0
	v_mov_b32_e32 v33, v137
	v_mov_b32_e32 v34, v137
	v_mov_b32_e32 v35, v137
	v_mov_b32_e32 v36, 0
	v_mov_b32_e32 v37, v137
	v_mov_b32_e32 v38, v137
	v_mov_b32_e32 v39, v137
	v_mov_b32_e32 v104, 0
	v_mov_b32_e32 v105, v137
	v_mov_b32_e32 v106, v137
	v_mov_b32_e32 v107, v137
	v_mov_b32_e32 v108, 0
	v_mov_b32_e32 v109, v137
	v_mov_b32_e32 v110, v137
	v_mov_b32_e32 v111, v137
	v_mov_b32_e32 v40, 0
	v_mov_b32_e32 v41, v137
	v_mov_b32_e32 v42, v137
	v_mov_b32_e32 v43, v137
	v_mov_b32_e32 v44, 0
	v_mov_b32_e32 v45, v137
	v_mov_b32_e32 v46, v137
	v_mov_b32_e32 v47, v137
	v_mov_b32_e32 v112, 0
	v_mov_b32_e32 v113, v137
	v_mov_b32_e32 v114, v137
	v_mov_b32_e32 v115, v137
	v_mov_b32_e32 v116, 0
	v_mov_b32_e32 v117, v137
	v_mov_b32_e32 v118, v137
	v_mov_b32_e32 v119, v137
	v_mov_b32_e32 v48, 0
	v_mov_b32_e32 v49, v137
	v_mov_b32_e32 v50, v137
	v_mov_b32_e32 v51, v137
	v_mov_b32_e32 v60, 0
	v_mov_b32_e32 v61, v137
	v_mov_b32_e32 v62, v137
	v_mov_b32_e32 v63, v137
	v_mov_b32_e32 v120, 0
	v_mov_b32_e32 v121, v137
	v_mov_b32_e32 v122, v137
	v_mov_b32_e32 v123, v137
	v_mov_b32_e32 v124, 0
	v_mov_b32_e32 v125, v137
	v_mov_b32_e32 v126, v137
	v_mov_b32_e32 v127, v137
	s_waitcnt vmcnt(0) lgkmcnt(0)
	s_barrier
	s_and_b32 s21, s13, 0x10000
	s_xor_b32 s24, s21, 0x10000
	s_add_i32 s24, s11, s24
	s_add_i32 s25, s24, 0x8000
	s_mov_b32 m0, s24
	v_lshl_add_u64 v[254:255], v[154:155], 0, s[6:7]
	global_load_lds_dwordx4 v[254:255], off
	s_add_i32 m0, s24, 0x2000
	v_lshl_add_u64 v[254:255], v[156:157], 0, s[6:7]
	global_load_lds_dwordx4 v[254:255], off
	s_add_i32 m0, s24, 0x4000
	v_lshl_add_u64 v[254:255], v[158:159], 0, s[6:7]
	global_load_lds_dwordx4 v[254:255], off
	s_add_i32 m0, s24, 0x6000
	v_lshl_add_u64 v[254:255], v[160:161], 0, s[6:7]
	global_load_lds_dwordx4 v[254:255], off
	s_mov_b32 m0, s25
	v_lshl_add_u64 v[254:255], v[162:163], 0, s[6:7]
	global_load_lds_dwordx4 v[254:255], off
	s_add_i32 m0, s24, 0xa000
	v_lshl_add_u64 v[254:255], v[164:165], 0, s[6:7]
	global_load_lds_dwordx4 v[254:255], off
	s_add_i32 m0, s24, 0xc000
	v_lshl_add_u64 v[254:255], v[166:167], 0, s[6:7]
	global_load_lds_dwordx4 v[254:255], off
	s_add_i32 m0, s24, 0xe000
	v_lshl_add_u64 v[254:255], v[168:169], 0, s[6:7]
	global_load_lds_dwordx4 v[254:255], off
	v_add3_u32 v253, s21, v141, v129
	ds_read_b128 v[206:209], v253 offset:0x1000
	ds_read_b128 v[210:213], v253 offset:0x1800
	ds_read_b128 v[198:201], v253 offset:0
	v_add3_u32 v253, s21, v143, v129
	ds_read_b128 v[170:173], v253 offset:0
	v_add3_u32 v253, s21, v141, v129
	ds_read_b128 v[202:205], v253 offset:0x800
	v_add3_u32 v253, s21, v143, v129
	ds_read_b128 v[174:177], v253 offset:0x800
	ds_read_b128 v[178:181], v253 offset:0x1000
	ds_read_b128 v[182:185], v253 offset:0x1800
	.p2align 6

.LBB0_1461:
	v_readfirstlane_b32 s11, v128
	s_lshr_b32 s12, s11, 1
	s_and_b32 s12, s12, 0x1ffff80
	s_lshl_b32 s0, s10, 19
	v_or_b32_e32 v5, s12, v189
	s_and_b32 s12, s11, 0xc0
	s_lshl_b32 s11, s11, 4
	v_add_u32_e32 v2, s0, v134
	v_lshlrev_b32_e32 v167, 7, v5
	v_or_b32_e32 v5, s12, v189
	s_and_b32 s11, s11, 0x7ffffc00
	v_add_u32_e32 v0, s0, v138
	v_lshl_or_b32 v203, v5, 7, v165
	v_and_b32_e32 v5, 0xfffff870, v2
	s_mov_b32 m0, s11
	v_add_u32_e32 v1, s0, v140
	global_load_lds_dwordx4 v5, s[86:87]
	v_and_b32_e32 v0, 0xfffff870, v0
	s_add_i32 m0, s11, 0x2000
	s_lshl_b32 s1, s30, 19
	v_add_u32_e32 v3, s0, v142
	global_load_lds_dwordx4 v0, s[86:87]
	v_and_b32_e32 v0, 0xfffff870, v1
	s_add_i32 m0, s11, 0x4000
	s_add_i32 s8, s1, 0x1080000
	global_load_lds_dwordx4 v0, s[86:87]
	v_and_b32_e32 v0, 0xfffff870, v3
	s_add_i32 m0, s11, 0x6000
	s_add_i32 s12, s11, 0x8000
	global_load_lds_dwordx4 v0, s[86:87]
	v_or_b32_e32 v0, s8, v144
	v_mov_b32_e32 v1, v145
	v_lshl_add_u64 v[0:1], s[86:87], 0, v[0:1]
	s_mov_b32 m0, s12
	v_add_u32_e32 v4, s1, v150
	global_load_lds_dwordx4 v[0:1], off
	v_or_b32_e32 v0, s8, v146
	v_mov_b32_e32 v1, v129
	v_lshl_add_u64 v[0:1], s[86:87], 0, v[0:1]
	s_add_i32 m0, s11, 0xa000
	v_and_b32_e32 v136, -16, v2
	global_load_lds_dwordx4 v[0:1], off
	v_or_b32_e32 v0, s8, v148
	v_mov_b32_e32 v1, v149
	v_lshl_add_u64 v[0:1], s[86:87], 0, v[0:1]
	s_add_i32 m0, s11, 0xc000
	v_lshl_add_u64 v[168:169], s[6:7], 0, v[136:137]
	global_load_lds_dwordx4 v[0:1], off
	v_and_b32_e32 v0, 0xfffff870, v4
	s_add_i32 m0, s11, 0xe000
	v_mov_b32_e32 v52, 0
	global_load_lds_dwordx4 v0, s[86:87]
	v_add_u32_e32 v0, s0, v152
	v_and_b32_e32 v136, -16, v0
	v_add_u32_e32 v0, s0, v154
	v_lshl_add_u64 v[170:171], s[6:7], 0, v[136:137]
	v_and_b32_e32 v136, -16, v0
	v_add_u32_e32 v0, s0, v156
	s_waitcnt vmcnt(0)
	v_lshl_add_u64 v[172:173], s[6:7], 0, v[136:137]
	v_and_b32_e32 v136, -16, v0
	v_add_u32_e32 v0, s1, v164
	v_lshl_add_u64 v[174:175], s[6:7], 0, v[136:137]
	v_and_b32_e32 v136, -16, v0
	v_lshl_add_u64 v[176:177], v[158:159], 0, s[8:9]
	v_lshl_add_u64 v[178:179], v[160:161], 0, s[8:9]
	v_lshl_add_u64 v[180:181], v[162:163], 0, s[8:9]
	v_lshl_add_u64 v[182:183], s[6:7], 0, v[136:137]
	s_mov_b32 s8, 0
	s_mov_b64 s[0:1], 0
	v_mov_b32_e32 v53, v52
	v_mov_b32_e32 v54, v52
	v_mov_b32_e32 v55, v52
	v_mov_b32_e32 v0, v52
	v_mov_b32_e32 v1, v52
	v_mov_b32_e32 v2, v52
	v_mov_b32_e32 v3, v52
	v_mov_b32_e32 v64, v52
	v_mov_b32_e32 v65, v52
	v_mov_b32_e32 v66, v52
	v_mov_b32_e32 v67, v52
	v_mov_b32_e32 v68, v52
	v_mov_b32_e32 v69, v52
	v_mov_b32_e32 v70, v52
	v_mov_b32_e32 v71, v52
	v_mov_b32_e32 v4, v52
	v_mov_b32_e32 v5, v52
	v_mov_b32_e32 v6, v52
	v_mov_b32_e32 v7, v52
	v_mov_b32_e32 v8, v52
	v_mov_b32_e32 v9, v52
	v_mov_b32_e32 v10, v52
	v_mov_b32_e32 v11, v52
	v_mov_b32_e32 v72, v52
	v_mov_b32_e32 v73, v52
	v_mov_b32_e32 v74, v52
	v_mov_b32_e32 v75, v52
	v_mov_b32_e32 v76, v52
	v_mov_b32_e32 v77, v52
	v_mov_b32_e32 v78, v52
	v_mov_b32_e32 v79, v52
	s_waitcnt vmcnt(0)
	v_mov_b32_e32 v12, v52
	v_mov_b32_e32 v13, v52
	v_mov_b32_e32 v14, v52
	v_mov_b32_e32 v15, v52
	v_mov_b32_e32 v16, v52
	v_mov_b32_e32 v17, v52
	v_mov_b32_e32 v18, v52
	v_mov_b32_e32 v19, v52
	v_mov_b32_e32 v80, v52
	v_mov_b32_e32 v81, v52
	v_mov_b32_e32 v82, v52
	v_mov_b32_e32 v83, v52
	v_mov_b32_e32 v84, v52
	v_mov_b32_e32 v85, v52
	v_mov_b32_e32 v86, v52
	v_mov_b32_e32 v87, v52
	v_mov_b32_e32 v20, v52
	v_mov_b32_e32 v21, v52
	v_mov_b32_e32 v22, v52
	v_mov_b32_e32 v23, v52
	v_mov_b32_e32 v24, v52
	v_mov_b32_e32 v25, v52
	v_mov_b32_e32 v26, v52
	v_mov_b32_e32 v27, v52
	v_mov_b32_e32 v88, v52
	v_mov_b32_e32 v89, v52
	v_mov_b32_e32 v90, v52
	v_mov_b32_e32 v91, v52
	v_mov_b32_e32 v92, v52
	v_mov_b32_e32 v93, v52
	v_mov_b32_e32 v94, v52
	v_mov_b32_e32 v95, v52
	v_mov_b32_e32 v28, v52
	v_mov_b32_e32 v29, v52
	v_mov_b32_e32 v30, v52
	v_mov_b32_e32 v31, v52
	v_mov_b32_e32 v32, v52
	v_mov_b32_e32 v33, v52
	v_mov_b32_e32 v34, v52
	v_mov_b32_e32 v35, v52
	v_mov_b32_e32 v96, v52
	v_mov_b32_e32 v97, v52
	v_mov_b32_e32 v98, v52
	v_mov_b32_e32 v99, v52
	v_mov_b32_e32 v100, v52
	v_mov_b32_e32 v101, v52
	v_mov_b32_e32 v102, v52
	v_mov_b32_e32 v103, v52
	v_mov_b32_e32 v36, v52
	v_mov_b32_e32 v37, v52
	v_mov_b32_e32 v38, v52
	v_mov_b32_e32 v39, v52
	v_mov_b32_e32 v40, v52
	v_mov_b32_e32 v41, v52
	v_mov_b32_e32 v42, v52
	v_mov_b32_e32 v43, v52
	v_mov_b32_e32 v104, v52
	v_mov_b32_e32 v105, v52
	v_mov_b32_e32 v106, v52
	v_mov_b32_e32 v107, v52
	v_mov_b32_e32 v108, v52
	v_mov_b32_e32 v109, v52
	v_mov_b32_e32 v110, v52
	v_mov_b32_e32 v111, v52
	v_mov_b32_e32 v44, v52
	v_mov_b32_e32 v45, v52
	v_mov_b32_e32 v46, v52
	v_mov_b32_e32 v47, v52
	v_mov_b32_e32 v48, v52
	v_mov_b32_e32 v49, v52
	v_mov_b32_e32 v50, v52
	v_mov_b32_e32 v51, v52
	v_mov_b32_e32 v112, v52
	v_mov_b32_e32 v113, v52
	v_mov_b32_e32 v114, v52
	v_mov_b32_e32 v115, v52
	v_mov_b32_e32 v116, v52
	v_mov_b32_e32 v117, v52
	v_mov_b32_e32 v118, v52
	v_mov_b32_e32 v119, v52
	v_mov_b32_e32 v56, v52
	v_mov_b32_e32 v57, v52
	v_mov_b32_e32 v58, v52
	v_mov_b32_e32 v59, v52
	v_mov_b32_e32 v60, v52
	v_mov_b32_e32 v61, v52
	v_mov_b32_e32 v62, v52
	v_mov_b32_e32 v63, v52
	v_mov_b32_e32 v120, v52
	v_mov_b32_e32 v121, v52
	v_mov_b32_e32 v122, v52
	v_mov_b32_e32 v123, v52
	v_mov_b32_e32 v124, v52
	v_mov_b32_e32 v125, v52
	v_mov_b32_e32 v126, v52
	v_mov_b32_e32 v127, v52
	s_waitcnt lgkmcnt(0)
	s_barrier
	s_mov_b32 s12, 0x10000
	s_and_b32 s12, s8, 0x10000
	s_xor_b32 s13, s12, 0x10000
	s_add_i32 s13, s11, s13
	s_add_i32 s31, s13, 0x8000
	s_mov_b32 m0, s13
	v_lshl_add_u64 v[254:255], v[168:169], 0, s[0:1]
	global_load_lds_dwordx4 v[254:255], off
	s_add_i32 m0, s13, 0x2000
	v_lshl_add_u64 v[254:255], v[170:171], 0, s[0:1]
	global_load_lds_dwordx4 v[254:255], off
	s_add_i32 m0, s13, 0x4000
	v_lshl_add_u64 v[254:255], v[172:173], 0, s[0:1]
	global_load_lds_dwordx4 v[254:255], off
	s_add_i32 m0, s13, 0x6000
	v_lshl_add_u64 v[254:255], v[174:175], 0, s[0:1]
	global_load_lds_dwordx4 v[254:255], off
	s_mov_b32 m0, s31
	v_lshl_add_u64 v[254:255], v[176:177], 0, s[0:1]
	global_load_lds_dwordx4 v[254:255], off
	s_add_i32 m0, s13, 0xa000
	v_lshl_add_u64 v[254:255], v[178:179], 0, s[0:1]
	global_load_lds_dwordx4 v[254:255], off
	s_add_i32 m0, s13, 0xc000
	v_lshl_add_u64 v[254:255], v[180:181], 0, s[0:1]
	global_load_lds_dwordx4 v[254:255], off
	s_add_i32 m0, s13, 0xe000
	v_lshl_add_u64 v[254:255], v[182:183], 0, s[0:1]
	global_load_lds_dwordx4 v[254:255], off
	v_add3_u32 v253, s12, v167, v139
	ds_read_b128 v[228:231], v253 offset:0x1000
	ds_read_b128 v[232:235], v253 offset:0x1800
	ds_read_b128 v[220:223], v253 offset:0
	v_add3_u32 v253, s12, v203, v139
	ds_read_b128 v[204:207], v253 offset:0
	v_add3_u32 v253, s12, v167, v139
	ds_read_b128 v[224:227], v253 offset:0x800
	v_add3_u32 v253, s12, v203, v139
	ds_read_b128 v[208:211], v253 offset:0x800
	ds_read_b128 v[212:215], v253 offset:0x1000
	ds_read_b128 v[216:219], v253 offset:0x1800
	.p2align 6

.LBB0_1857:
	s_ashr_i32 s0, s24, 31
	s_lshr_b32 s0, s0, 26
	s_add_i32 s0, s24, s0
	v_readfirstlane_b32 s13, v128
	s_ashr_i32 s14, s0, 6
	s_andn2_b32 s0, s0, 63
	s_lshr_b32 s15, s13, 1
	s_sub_i32 s12, s24, s0
	s_and_b32 s15, s15, 0x1ffff80
	s_lshl_b32 s0, s12, 19
	v_or_b32_e32 v5, s15, v189
	s_and_b32 s15, s13, 0xc0
	s_lshl_b32 s13, s13, 4
	v_add_u32_e32 v2, s0, v136
	v_lshlrev_b32_e32 v149, 7, v5
	v_or_b32_e32 v5, s15, v189
	s_and_b32 s13, s13, 0x7ffffc00
	v_add_u32_e32 v0, s0, v140
	v_lshl_or_b32 v153, v5, 7, v133
	v_and_b32_e32 v5, 0xfffff870, v2
	s_mov_b32 m0, s13
	v_add_u32_e32 v1, s0, v142
	global_load_lds_dwordx4 v5, s[86:87]
	v_and_b32_e32 v0, 0xfffff870, v0
	s_add_i32 m0, s13, 0x2000
	s_lshl_b32 s1, s14, 19
	v_add_u32_e32 v3, s0, v144
	global_load_lds_dwordx4 v0, s[86:87]
	v_and_b32_e32 v0, 0xfffff870, v1
	s_add_i32 m0, s13, 0x4000
	s_add_i32 s10, s1, 0x1700000
	global_load_lds_dwordx4 v0, s[86:87]
	v_and_b32_e32 v0, 0xfffff870, v3
	s_add_i32 m0, s13, 0x6000
	s_add_i32 s15, s13, 0x8000
	global_load_lds_dwordx4 v0, s[86:87]
	v_or_b32_e32 v0, s10, v146
	v_mov_b32_e32 v1, v147
	v_lshl_add_u64 v[0:1], s[86:87], 0, v[0:1]
	s_mov_b32 m0, s15
	v_add_u32_e32 v4, s1, v152
	global_load_lds_dwordx4 v[0:1], off
	v_or_b32_e32 v0, s10, v148
	v_mov_b32_e32 v1, v129
	v_lshl_add_u64 v[0:1], s[86:87], 0, v[0:1]
	s_add_i32 m0, s13, 0xa000
	v_and_b32_e32 v138, -16, v2
	global_load_lds_dwordx4 v[0:1], off
	v_or_b32_e32 v0, s10, v150
	v_mov_b32_e32 v1, v131
	v_lshl_add_u64 v[0:1], s[86:87], 0, v[0:1]
	s_add_i32 m0, s13, 0xc000
	v_lshl_add_u64 v[170:171], s[8:9], 0, v[138:139]
	global_load_lds_dwordx4 v[0:1], off
	v_and_or_b32 v0, v4, s17, v134
	v_mov_b32_e32 v1, v135
	v_lshl_add_u64 v[0:1], s[86:87], 0, v[0:1]
	s_add_i32 m0, s13, 0xe000
	v_lshl_add_u64 v[178:179], v[160:161], 0, s[10:11]
	global_load_lds_dwordx4 v[0:1], off
	v_add_u32_e32 v0, s0, v154
	v_and_b32_e32 v138, -16, v0
	v_add_u32_e32 v0, s0, v156
	v_lshl_add_u64 v[172:173], s[8:9], 0, v[138:139]
	v_and_b32_e32 v138, -16, v0
	v_add_u32_e32 v0, s0, v158
	s_waitcnt vmcnt(0)
	v_lshl_add_u64 v[174:175], s[8:9], 0, v[138:139]
	v_and_b32_e32 v138, -16, v0
	v_add_u32_e32 v0, s1, v168
	v_lshl_add_u64 v[176:177], s[8:9], 0, v[138:139]
	v_and_b32_e32 v138, 0xfffff800, v0
	v_lshl_add_u64 v[180:181], v[162:163], 0, s[10:11]
	v_lshl_add_u64 v[182:183], v[164:165], 0, s[10:11]
	v_lshl_add_u64 v[184:185], v[166:167], 0, v[138:139]
	s_mov_b64 s[0:1], 0
	s_mov_b32 s10, 0
	s_mov_b32 s15, 0
	v_mov_b32_e32 v56, 0
	v_mov_b32_e32 v57, v139
	v_mov_b32_e32 v58, v139
	v_mov_b32_e32 v59, v139
	v_mov_b32_e32 v52, 0
	v_mov_b32_e32 v53, v139
	v_mov_b32_e32 v54, v139
	v_mov_b32_e32 v55, v139
	s_waitcnt vmcnt(0)
	v_mov_b32_e32 v64, 0
	v_mov_b32_e32 v65, v139
	v_mov_b32_e32 v66, v139
	v_mov_b32_e32 v67, v139
	v_mov_b32_e32 v68, 0
	v_mov_b32_e32 v69, v139
	v_mov_b32_e32 v70, v139
	v_mov_b32_e32 v71, v139
	v_mov_b32_e32 v0, 0
	v_mov_b32_e32 v1, v139
	v_mov_b32_e32 v2, v139
	v_mov_b32_e32 v3, v139
	v_mov_b32_e32 v4, 0
	v_mov_b32_e32 v5, v139
	v_mov_b32_e32 v6, v139
	v_mov_b32_e32 v7, v139
	v_mov_b32_e32 v72, 0
	v_mov_b32_e32 v73, v139
	v_mov_b32_e32 v74, v139
	v_mov_b32_e32 v75, v139
	v_mov_b32_e32 v76, 0
	v_mov_b32_e32 v77, v139
	v_mov_b32_e32 v78, v139
	v_mov_b32_e32 v79, v139
	v_mov_b32_e32 v8, 0
	v_mov_b32_e32 v9, v139
	v_mov_b32_e32 v10, v139
	v_mov_b32_e32 v11, v139
	v_mov_b32_e32 v12, 0
	v_mov_b32_e32 v13, v139
	v_mov_b32_e32 v14, v139
	v_mov_b32_e32 v15, v139
	v_mov_b32_e32 v80, 0
	v_mov_b32_e32 v81, v139
	v_mov_b32_e32 v82, v139
	v_mov_b32_e32 v83, v139
	v_mov_b32_e32 v84, 0
	v_mov_b32_e32 v85, v139
	v_mov_b32_e32 v86, v139
	v_mov_b32_e32 v87, v139
	v_mov_b32_e32 v16, 0
	v_mov_b32_e32 v17, v139
	v_mov_b32_e32 v18, v139
	v_mov_b32_e32 v19, v139
	v_mov_b32_e32 v20, 0
	v_mov_b32_e32 v21, v139
	v_mov_b32_e32 v22, v139
	v_mov_b32_e32 v23, v139
	v_mov_b32_e32 v88, 0
	v_mov_b32_e32 v89, v139
	v_mov_b32_e32 v90, v139
	v_mov_b32_e32 v91, v139
	v_mov_b32_e32 v92, 0
	v_mov_b32_e32 v93, v139
	v_mov_b32_e32 v94, v139
	v_mov_b32_e32 v95, v139
	v_mov_b32_e32 v24, 0
	v_mov_b32_e32 v25, v139
	v_mov_b32_e32 v26, v139
	v_mov_b32_e32 v27, v139
	v_mov_b32_e32 v28, 0
	v_mov_b32_e32 v29, v139
	v_mov_b32_e32 v30, v139
	v_mov_b32_e32 v31, v139
	v_mov_b32_e32 v96, 0
	v_mov_b32_e32 v97, v139
	v_mov_b32_e32 v98, v139
	v_mov_b32_e32 v99, v139
	v_mov_b32_e32 v100, 0
	v_mov_b32_e32 v101, v139
	v_mov_b32_e32 v102, v139
	v_mov_b32_e32 v103, v139
	v_mov_b32_e32 v32, 0
	v_mov_b32_e32 v33, v139
	v_mov_b32_e32 v34, v139
	v_mov_b32_e32 v35, v139
	v_mov_b32_e32 v36, 0
	v_mov_b32_e32 v37, v139
	v_mov_b32_e32 v38, v139
	v_mov_b32_e32 v39, v139
	v_mov_b32_e32 v104, 0
	v_mov_b32_e32 v105, v139
	v_mov_b32_e32 v106, v139
	v_mov_b32_e32 v107, v139
	v_mov_b32_e32 v108, 0
	v_mov_b32_e32 v109, v139
	v_mov_b32_e32 v110, v139
	v_mov_b32_e32 v111, v139
	v_mov_b32_e32 v40, 0
	v_mov_b32_e32 v41, v139
	v_mov_b32_e32 v42, v139
	v_mov_b32_e32 v43, v139
	v_mov_b32_e32 v44, 0
	v_mov_b32_e32 v45, v139
	v_mov_b32_e32 v46, v139
	v_mov_b32_e32 v47, v139
	v_mov_b32_e32 v112, 0
	v_mov_b32_e32 v113, v139
	v_mov_b32_e32 v114, v139
	v_mov_b32_e32 v115, v139
	v_mov_b32_e32 v116, 0
	v_mov_b32_e32 v117, v139
	v_mov_b32_e32 v118, v139
	v_mov_b32_e32 v119, v139
	v_mov_b32_e32 v48, 0
	v_mov_b32_e32 v49, v139
	v_mov_b32_e32 v50, v139
	v_mov_b32_e32 v51, v139
	v_mov_b32_e32 v60, 0
	v_mov_b32_e32 v61, v139
	v_mov_b32_e32 v62, v139
	v_mov_b32_e32 v63, v139
	v_mov_b32_e32 v120, 0
	v_mov_b32_e32 v121, v139
	v_mov_b32_e32 v122, v139
	v_mov_b32_e32 v123, v139
	v_mov_b32_e32 v124, 0
	v_mov_b32_e32 v125, v139
	v_mov_b32_e32 v126, v139
	v_mov_b32_e32 v127, v139
	s_waitcnt lgkmcnt(0)
	s_barrier
	s_and_b32 s25, s10, 0x10000
	s_xor_b32 s26, s25, 0x10000
	s_add_i32 s26, s13, s26
	s_add_i32 s27, s26, 0x8000
	s_mov_b32 m0, s26
	v_lshl_add_u64 v[254:255], v[170:171], 0, s[0:1]
	global_load_lds_dwordx4 v[254:255], off
	s_add_i32 m0, s26, 0x2000
	v_lshl_add_u64 v[254:255], v[172:173], 0, s[0:1]
	global_load_lds_dwordx4 v[254:255], off
	s_add_i32 m0, s26, 0x4000
	v_lshl_add_u64 v[254:255], v[174:175], 0, s[0:1]
	global_load_lds_dwordx4 v[254:255], off
	s_add_i32 m0, s26, 0x6000
	v_lshl_add_u64 v[254:255], v[176:177], 0, s[0:1]
	global_load_lds_dwordx4 v[254:255], off
	s_mov_b32 m0, s27
	v_lshl_add_u64 v[254:255], v[178:179], 0, s[0:1]
	global_load_lds_dwordx4 v[254:255], off
	s_add_i32 m0, s26, 0xa000
	v_lshl_add_u64 v[254:255], v[180:181], 0, s[0:1]
	global_load_lds_dwordx4 v[254:255], off
	s_add_i32 m0, s26, 0xc000
	v_lshl_add_u64 v[254:255], v[182:183], 0, s[0:1]
	global_load_lds_dwordx4 v[254:255], off
	s_add_i32 m0, s26, 0xe000
	v_lshl_add_u64 v[254:255], v[184:185], 0, s[0:1]
	global_load_lds_dwordx4 v[254:255], off
	v_add3_u32 v253, s25, v149, v137
	ds_read_b128 v[224:227], v253 offset:0x1000
	ds_read_b128 v[228:231], v253 offset:0x1800
	ds_read_b128 v[216:219], v253 offset:0
	v_add3_u32 v253, s25, v153, v137
	ds_read_b128 v[200:203], v253 offset:0
	v_add3_u32 v253, s25, v149, v137
	ds_read_b128 v[220:223], v253 offset:0x800
	v_add3_u32 v253, s25, v153, v137
	ds_read_b128 v[204:207], v253 offset:0x800
	ds_read_b128 v[208:211], v253 offset:0x1000
	ds_read_b128 v[212:215], v253 offset:0x1800
	.p2align 6

.LBB0_1997:
	s_waitcnt vmcnt(4)
	v_add_u32_e32 v7, s21, v137
	v_cmp_gt_i32_e32 vcc, s25, v7
	v_mov_b32_e32 v0, 0
	v_mov_b32_e32 v4, 0x100
	v_mov_b32_e32 v5, 0x4000
	v_mov_b32_e32 v6, 0
	s_and_saveexec_b64 s[0:1], vcc
	v_mul_hi_i32 v4, v7, s16
	v_lshrrev_b32_e32 v5, 31, v4
	v_ashrrev_i32_e32 v4, 3, v4
	v_add_u32_e32 v4, v4, v5
	v_lshlrev_b32_e32 v5, 11, v4
	v_lshl_add_u32 v4, v4, 4, v4
	v_sub_u32_e32 v4, v7, v4
	v_mul_lo_u32 v6, v4, s26
	v_mov_b32_e32 v4, 0x800
	s_or_b64 exec, exec, s[0:1]
	s_mul_i32 s0, s7, 0x7e
	v_add_u32_e32 v7, s0, v129
	s_waitcnt vmcnt(2)
	v_add_u32_e32 v8, s33, v7
	v_lshl_add_u32 v10, v8, 11, v134
	v_mad_u64_u32 v[8:9], s[0:1], v3, s26, v[136:137]
	s_mul_i32 s1, s21, 0x7879
	s_lshr_b32 s7, s1, 31
	s_ashr_i32 s1, s1, 19
	s_add_i32 s1, s1, s7
	s_mul_i32 s7, s1, 17
	s_sub_i32 s7, s21, s7
	s_mulk_i32 s7, 0x7e
	s_sext_i32_i16 s7, s7
	v_add_u32_e32 v3, s7, v129
	v_lshl_add_u32 v9, s1, 11, v3
	v_add_u32_e32 v1, v8, v1
	v_lshl_add_u32 v9, v9, 11, v134
	v_cmp_gt_u32_e32 vcc, s27, v3
	v_lshl_add_u32 v1, v1, 11, v138
	v_readfirstlane_b32 s1, v128
	v_cndmask_b32_e32 v3, v147, v9, vcc
	v_cmp_lt_u32_e32 vcc, v8, v2
	v_subrev_u32_e32 v132, s86, v3
	v_add_u32_e32 v11, v139, v6
	v_cndmask_b32_e32 v1, v147, v1, vcc
	v_cmp_gt_u32_e32 vcc, s6, v7
	s_lshr_b32 s6, s1, 1
	s_and_b32 s6, s6, 0x1ffff80
	v_or_b32_e32 v3, s6, v189
	s_and_b32 s6, s1, 0xc0
	s_lshl_b32 s1, s1, 4
	s_and_b32 s33, s1, 0x7ffffc00
	v_add_u32_e32 v5, v11, v5
	s_mov_b32 m0, s33
	v_lshl_add_u32 v5, v5, 11, v142
	v_subrev_u32_e32 v2, s86, v1
	v_cndmask_b32_e32 v1, v147, v10, vcc
	v_cmp_lt_u32_e32 vcc, v11, v4
	global_load_lds_dwordx4 v132, s[86:87]
	s_add_i32 m0, s33, 0x2000
	s_lshl_b32 s0, s20, 19
	v_subrev_u32_e32 v6, s86, v1
	v_cndmask_b32_e32 v1, v147, v5, vcc
	global_load_lds_dwordx4 v2, s[86:87]
	s_add_i32 m0, s33, 0x4000
	v_subrev_u32_e32 v4, s86, v1
	v_lshlrev_b32_e32 v178, 7, v3
	v_or_b32_e32 v3, s6, v189
	s_add_i32 s6, s33, 0x8000
	global_load_lds_dwordx4 v6, s[86:87]
	s_add_i32 m0, s33, 0x6000
	v_or_b32_e32 v8, s0, v146
	v_mov_b32_e32 v9, v133
	global_load_lds_dwordx4 v4, s[86:87]
	v_lshl_add_u64 v[8:9], s[86:87], 0, v[8:9]
	s_mov_b32 m0, s6
	v_add_u32_e32 v1, s0, v150
	global_load_lds_dwordx4 v[8:9], off
	v_or_b32_e32 v8, s0, v148
	v_mov_b32_e32 v9, v133
	v_add_u32_e32 v10, s0, v144
	v_lshl_add_u64 v[8:9], s[86:87], 0, v[8:9]
	s_add_i32 m0, s33, 0xa000
	v_and_b32_e32 v1, 0xfffff870, v1
	global_load_lds_dwordx4 v[8:9], off
	s_add_i32 m0, s33, 0xc000
	v_and_or_b32 v8, v10, s28, v140
	v_mov_b32_e32 v9, v141
	global_load_lds_dwordx4 v1, s[86:87]
	v_lshl_add_u64 v[8:9], s[86:87], 0, v[8:9]
	s_add_i32 m0, s33, 0xe000
	v_add_u32_e32 v1, s0, v154
	global_load_lds_dwordx4 v[8:9], off
	s_waitcnt vmcnt(0)
	v_lshl_add_u64 v[160:161], s[18:19], 0, v[132:133]
	v_and_b32_e32 v132, -16, v1
	v_add_u32_e32 v1, s0, v158
	v_lshl_or_b32 v179, v3, 7, v149
	v_mov_b32_e32 v3, v133
	v_mov_b32_e32 v7, v133
	v_mov_b32_e32 v5, v133
	s_mov_b32 s1, 0
	v_lshl_add_u64 v[172:173], s[18:19], 0, v[132:133]
	v_and_b32_e32 v132, 0xfffff800, v1
	v_lshl_add_u64 v[162:163], s[18:19], 0, v[2:3]
	v_lshl_add_u64 v[164:165], s[18:19], 0, v[6:7]
	v_lshl_add_u64 v[166:167], s[18:19], 0, v[4:5]
	v_lshl_add_u64 v[168:169], v[152:153], 0, s[0:1]
	v_lshl_add_u64 v[170:171], v[130:131], 0, s[0:1]
	v_lshl_add_u64 v[174:175], v[156:157], 0, v[132:133]
	s_mov_b64 s[6:7], 0
	v_mov_b32_e32 v1, v0
	v_mov_b32_e32 v2, v0
	v_mov_b32_e32 v3, v0
	v_mov_b32_e32 v4, v0
	v_mov_b32_e32 v5, v0
	v_mov_b32_e32 v6, v0
	v_mov_b32_e32 v7, v0
	s_waitcnt vmcnt(0)
	v_mov_b32_e32 v64, v0
	v_mov_b32_e32 v65, v0
	v_mov_b32_e32 v66, v0
	v_mov_b32_e32 v67, v0
	v_mov_b32_e32 v68, v0
	v_mov_b32_e32 v69, v0
	v_mov_b32_e32 v70, v0
	v_mov_b32_e32 v71, v0
	v_mov_b32_e32 v8, v0
	v_mov_b32_e32 v9, v0
	v_mov_b32_e32 v10, v0
	v_mov_b32_e32 v11, v0
	v_mov_b32_e32 v12, v0
	v_mov_b32_e32 v13, v0
	v_mov_b32_e32 v14, v0
	v_mov_b32_e32 v15, v0
	v_mov_b32_e32 v72, v0
	v_mov_b32_e32 v73, v0
	v_mov_b32_e32 v74, v0
	v_mov_b32_e32 v75, v0
	v_mov_b32_e32 v76, v0
	v_mov_b32_e32 v77, v0
	v_mov_b32_e32 v78, v0
	v_mov_b32_e32 v79, v0
	v_mov_b32_e32 v16, v0
	v_mov_b32_e32 v17, v0
	v_mov_b32_e32 v18, v0
	v_mov_b32_e32 v19, v0
	v_mov_b32_e32 v20, v0
	v_mov_b32_e32 v21, v0
	v_mov_b32_e32 v22, v0
	v_mov_b32_e32 v23, v0
	v_mov_b32_e32 v80, v0
	v_mov_b32_e32 v81, v0
	v_mov_b32_e32 v82, v0
	v_mov_b32_e32 v83, v0
	v_mov_b32_e32 v84, v0
	v_mov_b32_e32 v85, v0
	v_mov_b32_e32 v86, v0
	v_mov_b32_e32 v87, v0
	v_mov_b32_e32 v24, v0
	v_mov_b32_e32 v25, v0
	v_mov_b32_e32 v26, v0
	v_mov_b32_e32 v27, v0
	v_mov_b32_e32 v28, v0
	v_mov_b32_e32 v29, v0
	v_mov_b32_e32 v30, v0
	v_mov_b32_e32 v31, v0
	v_mov_b32_e32 v88, v0
	v_mov_b32_e32 v89, v0
	v_mov_b32_e32 v90, v0
	v_mov_b32_e32 v91, v0
	v_mov_b32_e32 v92, v0
	v_mov_b32_e32 v93, v0
	v_mov_b32_e32 v94, v0
	v_mov_b32_e32 v95, v0
	v_mov_b32_e32 v32, v0
	v_mov_b32_e32 v33, v0
	v_mov_b32_e32 v34, v0
	v_mov_b32_e32 v35, v0
	v_mov_b32_e32 v36, v0
	v_mov_b32_e32 v37, v0
	v_mov_b32_e32 v38, v0
	v_mov_b32_e32 v39, v0
	v_mov_b32_e32 v96, v0
	v_mov_b32_e32 v97, v0
	v_mov_b32_e32 v98, v0
	v_mov_b32_e32 v99, v0
	v_mov_b32_e32 v100, v0
	v_mov_b32_e32 v101, v0
	v_mov_b32_e32 v102, v0
	v_mov_b32_e32 v103, v0
	v_mov_b32_e32 v40, v0
	v_mov_b32_e32 v41, v0
	v_mov_b32_e32 v42, v0
	v_mov_b32_e32 v43, v0
	v_mov_b32_e32 v44, v0
	v_mov_b32_e32 v45, v0
	v_mov_b32_e32 v46, v0
	v_mov_b32_e32 v47, v0
	v_mov_b32_e32 v104, v0
	v_mov_b32_e32 v105, v0
	v_mov_b32_e32 v106, v0
	v_mov_b32_e32 v107, v0
	v_mov_b32_e32 v108, v0
	v_mov_b32_e32 v109, v0
	v_mov_b32_e32 v110, v0
	v_mov_b32_e32 v111, v0
	v_mov_b32_e32 v48, v0
	v_mov_b32_e32 v49, v0
	v_mov_b32_e32 v50, v0
	v_mov_b32_e32 v51, v0
	v_mov_b32_e32 v52, v0
	v_mov_b32_e32 v53, v0
	v_mov_b32_e32 v54, v0
	v_mov_b32_e32 v55, v0
	v_mov_b32_e32 v112, v0
	v_mov_b32_e32 v113, v0
	v_mov_b32_e32 v114, v0
	v_mov_b32_e32 v115, v0
	v_mov_b32_e32 v116, v0
	v_mov_b32_e32 v117, v0
	v_mov_b32_e32 v118, v0
	v_mov_b32_e32 v119, v0
	v_mov_b32_e32 v56, v0
	v_mov_b32_e32 v57, v0
	v_mov_b32_e32 v58, v0
	v_mov_b32_e32 v59, v0
	v_mov_b32_e32 v60, v0
	v_mov_b32_e32 v61, v0
	v_mov_b32_e32 v62, v0
	v_mov_b32_e32 v63, v0
	v_mov_b32_e32 v120, v0
	v_mov_b32_e32 v121, v0
	v_mov_b32_e32 v122, v0
	v_mov_b32_e32 v123, v0
	v_mov_b32_e32 v124, v0
	v_mov_b32_e32 v125, v0
	v_mov_b32_e32 v126, v0
	v_mov_b32_e32 v127, v0
	s_waitcnt lgkmcnt(0)
	s_barrier
	s_mov_b32 s0, 0x10000
	s_and_b32 s0, s1, 0x10000
	s_xor_b32 s34, s0, 0x10000
	s_add_i32 s34, s33, s34
	s_add_i32 s35, s34, 0x8000
	s_mov_b32 m0, s34
	v_lshl_add_u64 v[254:255], v[160:161], 0, s[6:7]
	global_load_lds_dwordx4 v[254:255], off
	s_add_i32 m0, s34, 0x2000
	v_lshl_add_u64 v[254:255], v[162:163], 0, s[6:7]
	global_load_lds_dwordx4 v[254:255], off
	s_add_i32 m0, s34, 0x4000
	v_lshl_add_u64 v[254:255], v[164:165], 0, s[6:7]
	global_load_lds_dwordx4 v[254:255], off
	s_add_i32 m0, s34, 0x6000
	v_lshl_add_u64 v[254:255], v[166:167], 0, s[6:7]
	global_load_lds_dwordx4 v[254:255], off
	s_mov_b32 m0, s35
	v_lshl_add_u64 v[254:255], v[168:169], 0, s[6:7]
	global_load_lds_dwordx4 v[254:255], off
	s_add_i32 m0, s34, 0xa000
	v_lshl_add_u64 v[254:255], v[170:171], 0, s[6:7]
	global_load_lds_dwordx4 v[254:255], off
	s_add_i32 m0, s34, 0xc000
	v_lshl_add_u64 v[254:255], v[172:173], 0, s[6:7]
	global_load_lds_dwordx4 v[254:255], off
	s_add_i32 m0, s34, 0xe000
	v_lshl_add_u64 v[254:255], v[174:175], 0, s[6:7]
	global_load_lds_dwordx4 v[254:255], off
	v_add3_u32 v253, s0, v178, v143
	ds_read_b128 v[220:223], v253 offset:0x1000
	ds_read_b128 v[224:227], v253 offset:0x1800
	ds_read_b128 v[212:215], v253 offset:0
	v_add3_u32 v253, s0, v179, v143
	ds_read_b128 v[180:183], v253 offset:0
	v_add3_u32 v253, s0, v178, v143
	ds_read_b128 v[216:219], v253 offset:0x800
	v_add3_u32 v253, s0, v179, v143
	ds_read_b128 v[200:203], v253 offset:0x800
	ds_read_b128 v[204:207], v253 offset:0x1000
	ds_read_b128 v[208:211], v253 offset:0x1800
	.p2align 6

.LBB0_2081:
	s_ashr_i32 s0, s2, 31
	s_lshr_b32 s0, s0, 26
	s_add_i32 s0, s2, s0
	s_ashr_i32 s10, s0, 6
	s_andn2_b32 s0, s0, 63
	s_sub_i32 s8, s2, s0
	s_mul_i32 s0, s8, 0xb0000
	v_readfirstlane_b32 s9, v128
	s_lshl_b32 s11, s0, 1
	v_or_b32_e32 v3, s0, v130
	s_lshr_b32 s0, s9, 1
	s_and_b32 s0, s0, 0x1ffff80
	v_lshl_add_u32 v4, v3, 1, v140
	v_or_b32_e32 v3, s0, v189
	s_and_b32 s0, s9, 0xc0
	v_lshlrev_b32_e32 v137, 7, v3
	v_or_b32_e32 v3, s0, v189
	s_lshl_b32 s0, s9, 4
	v_add_u32_e32 v0, s11, v134
	s_and_b32 s9, s0, 0x7ffffc00
	v_add_u32_e32 v1, s11, v136
	v_and_b32_e32 v132, 0xfffffe70, v0
	s_mov_b32 m0, s9
	v_add_u32_e32 v2, s11, v138
	global_load_lds_dwordx4 v132, s[86:87]
	v_and_b32_e32 v0, 0xfffffe70, v1
	s_add_i32 m0, s9, 0x2000
	s_mul_i32 s1, s10, 0x160000
	global_load_lds_dwordx4 v0, s[86:87]
	v_and_b32_e32 v2, 0xfffffe70, v2
	s_add_i32 m0, s9, 0x4000
	v_add_u32_e32 v6, s1, v142
	s_add_i32 s0, s9, 0x8000
	global_load_lds_dwordx4 v2, s[86:87]
	v_and_b32_e32 v4, 0xfffffe70, v4
	s_add_i32 m0, s9, 0x6000
	v_add_u32_e32 v8, s1, v144
	s_waitcnt vmcnt(0)
	v_add_u32_e32 v12, s1, v148
	global_load_lds_dwordx4 v4, s[86:87]
	v_and_b32_e32 v6, 0xfffffe70, v6
	s_mov_b32 m0, s0
	v_add_u32_e32 v10, s1, v146
	global_load_lds_dwordx4 v6, s[86:87]
	v_and_b32_e32 v8, 0xfffffe70, v8
	s_add_i32 m0, s9, 0xa000
	v_and_b32_e32 v12, 0xfffffe00, v12
	global_load_lds_dwordx4 v8, s[86:87]
	v_and_b32_e32 v10, 0xfffffe70, v10
	s_add_i32 m0, s9, 0xc000
	v_or_b32_e32 v14, v150, v12
	v_mov_b32_e32 v15, v151
	global_load_lds_dwordx4 v10, s[86:87]
	v_lshl_add_u64 v[14:15], s[86:87], 0, v[14:15]
	s_add_i32 m0, s9, 0xe000
	v_lshl_or_b32 v139, v3, 7, v135
	global_load_lds_dwordx4 v[14:15], off
	s_waitcnt vmcnt(0)
	v_mov_b32_e32 v1, v133
	v_mov_b32_e32 v3, v133
	v_mov_b32_e32 v5, v133
	v_mov_b32_e32 v7, v133
	v_mov_b32_e32 v9, v133
	v_mov_b32_e32 v11, v133
	v_mov_b32_e32 v13, v133
	v_lshl_add_u64 v[154:155], s[6:7], 0, v[132:133]
	v_lshl_add_u64 v[156:157], s[6:7], 0, v[0:1]
	v_lshl_add_u64 v[158:159], s[6:7], 0, v[2:3]
	v_lshl_add_u64 v[160:161], s[6:7], 0, v[4:5]
	v_lshl_add_u64 v[162:163], s[6:7], 0, v[6:7]
	v_lshl_add_u64 v[164:165], s[6:7], 0, v[8:9]
	v_lshl_add_u64 v[166:167], s[6:7], 0, v[10:11]
	v_lshl_add_u64 v[168:169], v[152:153], 0, v[12:13]
	s_mov_b64 s[0:1], 0
	s_mov_b32 s11, 0
	s_mov_b32 s16, 0
	v_mov_b32_e32 v56, 0
	v_mov_b32_e32 v57, v133
	v_mov_b32_e32 v58, v133
	v_mov_b32_e32 v59, v133
	v_mov_b32_e32 v52, 0
	v_mov_b32_e32 v53, v133
	v_mov_b32_e32 v54, v133
	v_mov_b32_e32 v55, v133
	v_mov_b32_e32 v64, 0
	v_mov_b32_e32 v65, v133
	v_mov_b32_e32 v66, v133
	v_mov_b32_e32 v67, v133
	v_mov_b32_e32 v68, 0
	v_mov_b32_e32 v69, v133
	v_mov_b32_e32 v70, v133
	v_mov_b32_e32 v71, v133
	v_mov_b32_e32 v0, 0
	v_mov_b32_e32 v2, v133
	v_mov_b32_e32 v4, 0
	v_mov_b32_e32 v6, v133
	v_mov_b32_e32 v72, 0
	v_mov_b32_e32 v73, v133
	v_mov_b32_e32 v74, v133
	v_mov_b32_e32 v75, v133
	v_mov_b32_e32 v76, 0
	v_mov_b32_e32 v77, v133
	v_mov_b32_e32 v78, v133
	v_mov_b32_e32 v79, v133
	v_mov_b32_e32 v8, 0
	v_mov_b32_e32 v10, v133
	v_mov_b32_e32 v12, 0
	v_mov_b32_e32 v14, v133
	v_mov_b32_e32 v15, v133
	v_mov_b32_e32 v80, 0
	v_mov_b32_e32 v81, v133
	v_mov_b32_e32 v82, v133
	v_mov_b32_e32 v83, v133
	v_mov_b32_e32 v84, 0
	v_mov_b32_e32 v85, v133
	v_mov_b32_e32 v86, v133
	v_mov_b32_e32 v87, v133
	v_mov_b32_e32 v16, 0
	v_mov_b32_e32 v17, v133
	v_mov_b32_e32 v18, v133
	v_mov_b32_e32 v19, v133
	v_mov_b32_e32 v20, 0
	v_mov_b32_e32 v21, v133
	v_mov_b32_e32 v22, v133
	v_mov_b32_e32 v23, v133
	v_mov_b32_e32 v88, 0
	v_mov_b32_e32 v89, v133
	v_mov_b32_e32 v90, v133
	v_mov_b32_e32 v91, v133
	v_mov_b32_e32 v92, 0
	v_mov_b32_e32 v93, v133
	v_mov_b32_e32 v94, v133
	v_mov_b32_e32 v95, v133
	v_mov_b32_e32 v24, 0
	v_mov_b32_e32 v25, v133
	v_mov_b32_e32 v26, v133
	v_mov_b32_e32 v27, v133
	v_mov_b32_e32 v28, 0
	v_mov_b32_e32 v29, v133
	v_mov_b32_e32 v30, v133
	v_mov_b32_e32 v31, v133
	v_mov_b32_e32 v96, 0
	v_mov_b32_e32 v97, v133
	v_mov_b32_e32 v98, v133
	v_mov_b32_e32 v99, v133
	v_mov_b32_e32 v100, 0
	v_mov_b32_e32 v101, v133
	v_mov_b32_e32 v102, v133
	v_mov_b32_e32 v103, v133
	v_mov_b32_e32 v32, 0
	v_mov_b32_e32 v33, v133
	v_mov_b32_e32 v34, v133
	v_mov_b32_e32 v35, v133
	v_mov_b32_e32 v36, 0
	v_mov_b32_e32 v37, v133
	v_mov_b32_e32 v38, v133
	v_mov_b32_e32 v39, v133
	v_mov_b32_e32 v104, 0
	v_mov_b32_e32 v105, v133
	v_mov_b32_e32 v106, v133
	v_mov_b32_e32 v107, v133
	v_mov_b32_e32 v108, 0
	v_mov_b32_e32 v109, v133
	v_mov_b32_e32 v110, v133
	v_mov_b32_e32 v111, v133
	v_mov_b32_e32 v40, 0
	v_mov_b32_e32 v41, v133
	v_mov_b32_e32 v42, v133
	v_mov_b32_e32 v43, v133
	v_mov_b32_e32 v44, 0
	v_mov_b32_e32 v45, v133
	v_mov_b32_e32 v46, v133
	v_mov_b32_e32 v47, v133
	v_mov_b32_e32 v112, 0
	v_mov_b32_e32 v113, v133
	v_mov_b32_e32 v114, v133
	v_mov_b32_e32 v115, v133
	v_mov_b32_e32 v116, 0
	v_mov_b32_e32 v117, v133
	v_mov_b32_e32 v118, v133
	v_mov_b32_e32 v119, v133
	v_mov_b32_e32 v48, 0
	v_mov_b32_e32 v49, v133
	v_mov_b32_e32 v50, v133
	v_mov_b32_e32 v51, v133
	v_mov_b32_e32 v60, 0
	v_mov_b32_e32 v61, v133
	v_mov_b32_e32 v62, v133
	v_mov_b32_e32 v63, v133
	v_mov_b32_e32 v120, 0
	v_mov_b32_e32 v121, v133
	v_mov_b32_e32 v122, v133
	v_mov_b32_e32 v123, v133
	v_mov_b32_e32 v124, 0
	v_mov_b32_e32 v125, v133
	v_mov_b32_e32 v126, v133
	v_mov_b32_e32 v127, v133
	s_waitcnt vmcnt(0) lgkmcnt(0)
	s_barrier
	s_and_b32 s17, s11, 0x10000
	s_xor_b32 s18, s17, 0x10000
	s_add_i32 s18, s9, s18
	s_add_i32 s19, s18, 0x8000
	s_mov_b32 m0, s18
	v_lshl_add_u64 v[254:255], v[154:155], 0, s[0:1]
	global_load_lds_dwordx4 v[254:255], off
	s_add_i32 m0, s18, 0x2000
	v_lshl_add_u64 v[254:255], v[156:157], 0, s[0:1]
	global_load_lds_dwordx4 v[254:255], off
	s_add_i32 m0, s18, 0x4000
	v_lshl_add_u64 v[254:255], v[158:159], 0, s[0:1]
	global_load_lds_dwordx4 v[254:255], off
	s_add_i32 m0, s18, 0x6000
	v_lshl_add_u64 v[254:255], v[160:161], 0, s[0:1]
	global_load_lds_dwordx4 v[254:255], off
	s_mov_b32 m0, s19
	v_lshl_add_u64 v[254:255], v[162:163], 0, s[0:1]
	global_load_lds_dwordx4 v[254:255], off
	s_add_i32 m0, s18, 0xa000
	v_lshl_add_u64 v[254:255], v[164:165], 0, s[0:1]
	global_load_lds_dwordx4 v[254:255], off
	s_add_i32 m0, s18, 0xc000
	v_lshl_add_u64 v[254:255], v[166:167], 0, s[0:1]
	global_load_lds_dwordx4 v[254:255], off
	s_add_i32 m0, s18, 0xe000
	v_lshl_add_u64 v[254:255], v[168:169], 0, s[0:1]
	global_load_lds_dwordx4 v[254:255], off
	v_add3_u32 v253, s17, v137, v129
	ds_read_b128 v[198:201], v253 offset:0x1000
	ds_read_b128 v[202:205], v253 offset:0x1800
	ds_read_b128 v[190:193], v253 offset:0
	v_add3_u32 v253, s17, v139, v129
	ds_read_b128 v[170:173], v253 offset:0
	v_add3_u32 v253, s17, v137, v129
	ds_read_b128 v[194:197], v253 offset:0x800
	v_add3_u32 v253, s17, v139, v129
	ds_read_b128 v[174:177], v253 offset:0x800
	ds_read_b128 v[178:181], v253 offset:0x1000
	ds_read_b128 v[182:185], v253 offset:0x1800
	.p2align 6
